# v21 + grid barriers: L1 invalidate (buffer_inv sc1) issued at arrival instead of after the release (no cached loads occur on the barrier path)
# speedup vs baseline: 1.0497x; 1.0160x over previous
; __device__ __forceinline__ unsigned xb_ld(unsigned* p)              { return __hip_atomic_load(p, __ATOMIC_RELAXED, __HIP_MEMORY_SCOPE_AGENT); }
; __device__ __forceinline__ unsigned xb_add(unsigned* p, unsigned v) { return __hip_atomic_fetch_add(p, v, __ATOMIC_RELAXED, __HIP_MEMORY_SCOPE_AGENT); }
; #define XB_SPIN(cond, bar) do { unsigned _sp = 0; while (cond) { __builtin_amdgcn_s_sleep(1); \
;     if ((++_sp & 255u) == 0u) { if (xb_ld(&(bar)[XB_TMO])) break; if (_sp > XB_SPIN_CAP) { atomicAdd(&(bar)[XB_TMO], 1u); break; } } } } while (0)
; __device__ __forceinline__ void xcd_barrier(const XcdBarrier& b) {
;     ...
;         const unsigned old = xb_add(&bar[XB_XSUB(b.x)], 1u);
;         const unsigned gen = old / nloc;
;         if (old + 1u == (gen + 1u) * nloc) {
;     ...
;             XB_SPIN(xb_ld(&bar[XB_XGEN(b.x)]) == gen, bar);
.LBB0_171:
	s_or_b64 exec, exec, s[8:9]
	v_cvt_f32_u32_e32 v4, v2
	s_waitcnt vmcnt(0)
	v_readfirstlane_b32 s3, v3
	v_sub_u32_e32 v3, 0, v2
	v_rcp_iflag_f32_e32 v4, v4
	v_add_u32_e32 v5, s3, v1
	v_mul_f32_e32 v4, 0x4f7ffffe, v4
	v_cvt_u32_f32_e32 v4, v4
	v_mul_lo_u32 v1, v3, v4
	v_mul_hi_u32 v1, v4, v1
	v_add_u32_e32 v1, v4, v1
	v_mul_hi_u32 v1, v5, v1
	v_mul_lo_u32 v3, v1, v2
	v_sub_u32_e32 v3, v5, v3
	v_add_u32_e32 v4, 1, v1
	v_cmp_ge_u32_e32 vcc, v3, v2
	s_nop 1
	v_cndmask_b32_e32 v1, v1, v4, vcc
	v_sub_u32_e32 v4, v3, v2
	v_cndmask_b32_e32 v3, v3, v4, vcc
	v_add_u32_e32 v4, 1, v1
	v_cmp_ge_u32_e32 vcc, v3, v2
	v_add_u32_e32 v3, 1, v5
	s_nop 0
	v_cndmask_b32_e32 v1, v1, v4, vcc
	v_mul_lo_u32 v4, v2, v1
	v_add_u32_e32 v2, v4, v2
	v_cmp_ne_u32_e32 vcc, v3, v2
	s_and_saveexec_b64 s[6:7], vcc
	s_xor_b64 s[6:7], exec, s[6:7]
	s_cbranch_execz .LBB0_185
	s_waitcnt lgkmcnt(0)
	v_mov_b32_e32 v0, 0x2000
	global_load_dword v0, v0, s[4:5] offset:1024 sc1
	buffer_inv sc1
	s_add_u32 s12, s4, 0x2400
	s_addc_u32 s13, s5, 0
	s_waitcnt vmcnt(0)
	v_cmp_eq_u32_e32 vcc, v0, v1
	s_and_saveexec_b64 s[8:9], vcc
	s_cbranch_execz .LBB0_184
	s_add_u32 s10, s70, 0x4200
	s_addc_u32 s11, s71, 0
	s_mov_b32 s3, 1
	s_mov_b64 s[14:15], 0
	v_mov_b32_e32 v0, 0
	s_branch .LBB0_175

; __device__ __forceinline__ unsigned xb_ld(unsigned* p)              { return __hip_atomic_load(p, __ATOMIC_RELAXED, __HIP_MEMORY_SCOPE_AGENT); }
; __device__ __forceinline__ unsigned xb_add(unsigned* p, unsigned v) { return __hip_atomic_fetch_add(p, v, __ATOMIC_RELAXED, __HIP_MEMORY_SCOPE_AGENT); }
; #define XB_SPIN(cond, bar) do { unsigned _sp = 0; while (cond) { __builtin_amdgcn_s_sleep(1); \
;     if ((++_sp & 255u) == 0u) { if (xb_ld(&(bar)[XB_TMO])) break; if (_sp > XB_SPIN_CAP) { atomicAdd(&(bar)[XB_TMO], 1u); break; } } } } while (0)
; __device__ __forceinline__ void xcd_barrier(const XcdBarrier& b) {
;     ...
;             __builtin_amdgcn_fence(__ATOMIC_RELEASE, "agent");
;             asm volatile("s_waitcnt vmcnt(0)" ::: "memory");
;             const unsigned og = xb_add(&bar[XB_TOP], 1u);
;     ...
;             XB_SPIN(xb_ld(&bar[XB_XGEN(b.x)]) == gen, bar);
;             __builtin_amdgcn_fence(__ATOMIC_ACQUIRE, "agent");
;             asm volatile("s_waitcnt vmcnt(0)" ::: "memory");
.LBB0_184:
	s_or_b64 exec, exec, s[8:9]
	s_waitcnt vmcnt(0)
	s_waitcnt vmcnt(0)
.LBB0_185:
	s_andn2_saveexec_b64 s[6:7], s[6:7]
	s_cbranch_execz .LBB0_205
	s_mov_b64 s[6:7], exec
	buffer_wbl2 sc1
	buffer_inv sc1
	s_waitcnt lgkmcnt(0)
	s_waitcnt vmcnt(0)
	v_mbcnt_lo_u32_b32 v1, s6, 0
	v_mbcnt_hi_u32_b32 v1, s7, v1
	v_cmp_eq_u32_e32 vcc, 0, v1
	s_and_saveexec_b64 s[8:9], vcc
	s_cbranch_execz .LBB0_188
	s_bcnt1_i32_b64 s3, s[6:7]
	v_mov_b32_e32 v2, 0x7000
	v_mov_b32_e32 v3, s3
	global_atomic_add v2, v2, v3, s[70:71] offset:1024 sc0

; __device__ __forceinline__ unsigned xb_ld(unsigned* p)              { return __hip_atomic_load(p, __ATOMIC_RELAXED, __HIP_MEMORY_SCOPE_AGENT); }
; __device__ __forceinline__ unsigned xb_add(unsigned* p, unsigned v) { return __hip_atomic_fetch_add(p, v, __ATOMIC_RELAXED, __HIP_MEMORY_SCOPE_AGENT); }
; #define XB_SPIN(cond, bar) do { unsigned _sp = 0; while (cond) { __builtin_amdgcn_s_sleep(1); \
;     if ((++_sp & 255u) == 0u) { if (xb_ld(&(bar)[XB_TMO])) break; if (_sp > XB_SPIN_CAP) { atomicAdd(&(bar)[XB_TMO], 1u); break; } } } } while (0)
; __device__ __forceinline__ void xcd_barrier(const XcdBarrier& b) {
;     ...
;             else XB_SPIN(xb_ld(&bar[XB_TOPGEN]) == tg, bar);
;             __builtin_amdgcn_fence(__ATOMIC_ACQUIRE, "agent");
;             xb_add(&bar[XB_XGEN(b.x)], 1u);
.LBB0_202:
	s_or_b64 exec, exec, s[6:7]
	s_mov_b64 s[6:7], exec
	v_mbcnt_lo_u32_b32 v0, s6, 0
	v_mbcnt_hi_u32_b32 v0, s7, v0
	v_cmp_eq_u32_e32 vcc, 0, v0
	s_waitcnt vmcnt(0)
	s_and_saveexec_b64 s[8:9], vcc
	s_cbranch_execz .LBB0_204
	s_bcnt1_i32_b64 s3, s[6:7]
	v_mov_b32_e32 v0, 0x2000
	v_mov_b32_e32 v1, s3
	global_atomic_add v0, v1, s[4:5] offset:1024

; __device__ __forceinline__ unsigned xb_ld(unsigned* p)              { return __hip_atomic_load(p, __ATOMIC_RELAXED, __HIP_MEMORY_SCOPE_AGENT); }
; __device__ __forceinline__ unsigned xb_add(unsigned* p, unsigned v) { return __hip_atomic_fetch_add(p, v, __ATOMIC_RELAXED, __HIP_MEMORY_SCOPE_AGENT); }
; #define XB_SPIN(cond, bar) do { unsigned _sp = 0; while (cond) { __builtin_amdgcn_s_sleep(1); \
;     if ((++_sp & 255u) == 0u) { if (xb_ld(&(bar)[XB_TMO])) break; if (_sp > XB_SPIN_CAP) { atomicAdd(&(bar)[XB_TMO], 1u); break; } } } } while (0)
; __device__ __forceinline__ void xcd_barrier(const XcdBarrier& b) {
;     ...
;         const unsigned old = xb_add(&bar[XB_XSUB(b.x)], 1u);
;         const unsigned gen = old / nloc;
;         if (old + 1u == (gen + 1u) * nloc) {
;     ...
;             XB_SPIN(xb_ld(&bar[XB_XGEN(b.x)]) == gen, bar);
.LBB0_294:
	s_or_b64 exec, exec, s[8:9]
	v_cvt_f32_u32_e32 v21, v3
	s_waitcnt vmcnt(0)
	v_readfirstlane_b32 s6, v20
	v_sub_u32_e32 v20, 0, v3
	v_rcp_iflag_f32_e32 v21, v21
	v_add_u32_e32 v22, s6, v0
	v_mul_f32_e32 v21, 0x4f7ffffe, v21
	v_cvt_u32_f32_e32 v21, v21
	v_mul_lo_u32 v0, v20, v21
	v_mul_hi_u32 v0, v21, v0
	v_add_u32_e32 v0, v21, v0
	v_mul_hi_u32 v0, v22, v0
	v_mul_lo_u32 v20, v0, v3
	v_sub_u32_e32 v20, v22, v20
	v_add_u32_e32 v21, 1, v0
	v_cmp_ge_u32_e32 vcc, v20, v3
	s_nop 1
	v_cndmask_b32_e32 v0, v0, v21, vcc
	v_sub_u32_e32 v21, v20, v3
	v_cndmask_b32_e32 v20, v20, v21, vcc
	v_add_u32_e32 v21, 1, v0
	v_cmp_ge_u32_e32 vcc, v20, v3
	v_add_u32_e32 v20, 1, v22
	s_nop 0
	v_cndmask_b32_e32 v0, v0, v21, vcc
	v_mul_lo_u32 v21, v3, v0
	v_add_u32_e32 v3, v21, v3
	v_cmp_ne_u32_e32 vcc, v20, v3
	s_and_saveexec_b64 s[6:7], vcc
	s_xor_b64 s[6:7], exec, s[6:7]
	s_cbranch_execz .LBB0_308
	s_waitcnt lgkmcnt(0)
	v_mov_b32_e32 v2, 0x2000
	global_load_dword v2, v2, s[4:5] offset:1024 sc1
	buffer_inv sc1
	s_add_u32 s10, s4, 0x2400
	s_addc_u32 s11, s5, 0
	s_waitcnt vmcnt(0)
	v_cmp_eq_u32_e32 vcc, v2, v0
	s_and_saveexec_b64 s[8:9], vcc
	s_cbranch_execz .LBB0_307
	s_mov_b32 s22, 1
	s_mov_b64 s[12:13], 0
	s_branch .LBB0_298

; __device__ __forceinline__ unsigned xb_add(unsigned* p, unsigned v) { return __hip_atomic_fetch_add(p, v, __ATOMIC_RELAXED, __HIP_MEMORY_SCOPE_AGENT); }
; __device__ __forceinline__ void xcd_barrier(const XcdBarrier& b) {
;     ...
;         if (old + 1u == (gen + 1u) * nloc) {
;             __builtin_amdgcn_fence(__ATOMIC_RELEASE, "agent");
;             asm volatile("s_waitcnt vmcnt(0)" ::: "memory");
;             const unsigned og = xb_add(&bar[XB_TOP], 1u);
.LBB0_308:
	s_andn2_saveexec_b64 s[6:7], s[6:7]
	s_cbranch_execz .LBB0_328
	s_mov_b64 s[6:7], exec
	buffer_wbl2 sc1
	buffer_inv sc1
	s_waitcnt lgkmcnt(0)
	s_waitcnt vmcnt(0)
	v_mbcnt_lo_u32_b32 v0, s6, 0
	v_mbcnt_hi_u32_b32 v0, s7, v0
	v_cmp_eq_u32_e32 vcc, 0, v0
	s_and_saveexec_b64 s[8:9], vcc
	s_cbranch_execz .LBB0_311
	s_bcnt1_i32_b64 s6, s[6:7]
	v_mov_b32_e32 v3, s6
	v_readlane_b32 s6, v253, 26
	v_readlane_b32 s7, v253, 27
	s_nop 4
	global_atomic_add v3, v1, v3, s[6:7] sc0

; __device__ __forceinline__ unsigned xb_ld(unsigned* p)              { return __hip_atomic_load(p, __ATOMIC_RELAXED, __HIP_MEMORY_SCOPE_AGENT); }
; __device__ __forceinline__ unsigned xb_add(unsigned* p, unsigned v) { return __hip_atomic_fetch_add(p, v, __ATOMIC_RELAXED, __HIP_MEMORY_SCOPE_AGENT); }
; #define XB_SPIN(cond, bar) do { unsigned _sp = 0; while (cond) { __builtin_amdgcn_s_sleep(1); \
;     if ((++_sp & 255u) == 0u) { if (xb_ld(&(bar)[XB_TMO])) break; if (_sp > XB_SPIN_CAP) { atomicAdd(&(bar)[XB_TMO], 1u); break; } } } } while (0)
; __device__ __forceinline__ void xcd_barrier(const XcdBarrier& b) {
;     ...
;             else XB_SPIN(xb_ld(&bar[XB_TOPGEN]) == tg, bar);
;             __builtin_amdgcn_fence(__ATOMIC_ACQUIRE, "agent");
;             xb_add(&bar[XB_XGEN(b.x)], 1u);
.LBB0_325:
	s_or_b64 exec, exec, s[6:7]
	s_mov_b64 s[6:7], exec
	v_mbcnt_lo_u32_b32 v0, s6, 0
	v_mbcnt_hi_u32_b32 v0, s7, v0
	v_cmp_eq_u32_e32 vcc, 0, v0
	s_waitcnt vmcnt(0)
	s_and_saveexec_b64 s[8:9], vcc
	s_cbranch_execz .LBB0_327
	s_bcnt1_i32_b64 s6, s[6:7]
	v_mov_b32_e32 v0, s6
	v_mov_b32_e32 v2, 0x2000
	global_atomic_add v2, v0, s[4:5] offset:1024

; __device__ __forceinline__ unsigned xb_ld(unsigned* p)              { return __hip_atomic_load(p, __ATOMIC_RELAXED, __HIP_MEMORY_SCOPE_AGENT); }
; __device__ __forceinline__ unsigned xb_add(unsigned* p, unsigned v) { return __hip_atomic_fetch_add(p, v, __ATOMIC_RELAXED, __HIP_MEMORY_SCOPE_AGENT); }
; #define XB_SPIN(cond, bar) do { unsigned _sp = 0; while (cond) { __builtin_amdgcn_s_sleep(1); \
;     if ((++_sp & 255u) == 0u) { if (xb_ld(&(bar)[XB_TMO])) break; if (_sp > XB_SPIN_CAP) { atomicAdd(&(bar)[XB_TMO], 1u); break; } } } } while (0)
; __device__ __forceinline__ void xcd_barrier(const XcdBarrier& b) {
;     ...
;         const unsigned old = xb_add(&bar[XB_XSUB(b.x)], 1u);
;         const unsigned gen = old / nloc;
;         if (old + 1u == (gen + 1u) * nloc) {
;     ...
;             XB_SPIN(xb_ld(&bar[XB_XGEN(b.x)]) == gen, bar);
.LBB0_395:
	s_or_b64 exec, exec, s[14:15]
	v_cvt_f32_u32_e32 v21, v3
	s_waitcnt vmcnt(0)
	v_readfirstlane_b32 s12, v20
	v_sub_u32_e32 v20, 0, v3
	v_rcp_iflag_f32_e32 v21, v21
	v_add_u32_e32 v22, s12, v0
	v_mul_f32_e32 v21, 0x4f7ffffe, v21
	v_cvt_u32_f32_e32 v21, v21
	v_mul_lo_u32 v0, v20, v21
	v_mul_hi_u32 v0, v21, v0
	v_add_u32_e32 v0, v21, v0
	v_mul_hi_u32 v0, v22, v0
	v_mul_lo_u32 v20, v0, v3
	v_sub_u32_e32 v20, v22, v20
	v_add_u32_e32 v21, 1, v0
	v_cmp_ge_u32_e32 vcc, v20, v3
	s_nop 1
	v_cndmask_b32_e32 v0, v0, v21, vcc
	v_sub_u32_e32 v21, v20, v3
	v_cndmask_b32_e32 v20, v20, v21, vcc
	v_add_u32_e32 v21, 1, v0
	v_cmp_ge_u32_e32 vcc, v20, v3
	v_add_u32_e32 v20, 1, v22
	s_nop 0
	v_cndmask_b32_e32 v0, v0, v21, vcc
	v_mul_lo_u32 v21, v3, v0
	v_add_u32_e32 v3, v21, v3
	v_cmp_ne_u32_e32 vcc, v20, v3
	s_and_saveexec_b64 s[12:13], vcc
	s_xor_b64 s[12:13], exec, s[12:13]
	s_cbranch_execz .LBB0_409
	s_waitcnt lgkmcnt(0)
	v_mov_b32_e32 v2, 0x2000
	global_load_dword v2, v2, s[10:11] offset:1024 sc1
	buffer_inv sc1
	s_add_u32 s16, s10, 0x2400
	s_addc_u32 s17, s11, 0
	s_waitcnt vmcnt(0)
	v_cmp_eq_u32_e32 vcc, v2, v0
	s_and_saveexec_b64 s[14:15], vcc
	s_cbranch_execz .LBB0_408
	s_mov_b32 s22, 1
	s_mov_b64 s[18:19], 0
	s_branch .LBB0_399

; __device__ __forceinline__ unsigned xb_ld(unsigned* p)              { return __hip_atomic_load(p, __ATOMIC_RELAXED, __HIP_MEMORY_SCOPE_AGENT); }
; __device__ __forceinline__ unsigned xb_add(unsigned* p, unsigned v) { return __hip_atomic_fetch_add(p, v, __ATOMIC_RELAXED, __HIP_MEMORY_SCOPE_AGENT); }
; #define XB_SPIN(cond, bar) do { unsigned _sp = 0; while (cond) { __builtin_amdgcn_s_sleep(1); \
;     if ((++_sp & 255u) == 0u) { if (xb_ld(&(bar)[XB_TMO])) break; if (_sp > XB_SPIN_CAP) { atomicAdd(&(bar)[XB_TMO], 1u); break; } } } } while (0)
; __device__ __forceinline__ void xcd_barrier(const XcdBarrier& b) {
;     ...
;             __builtin_amdgcn_fence(__ATOMIC_RELEASE, "agent");
;             asm volatile("s_waitcnt vmcnt(0)" ::: "memory");
;             const unsigned og = xb_add(&bar[XB_TOP], 1u);
;     ...
;             XB_SPIN(xb_ld(&bar[XB_XGEN(b.x)]) == gen, bar);
;             __builtin_amdgcn_fence(__ATOMIC_ACQUIRE, "agent");
;             asm volatile("s_waitcnt vmcnt(0)" ::: "memory");
.LBB0_408:
	s_or_b64 exec, exec, s[14:15]
	s_waitcnt vmcnt(0)
	s_waitcnt vmcnt(0)
.LBB0_409:
	s_andn2_saveexec_b64 s[12:13], s[12:13]
	s_cbranch_execz .LBB0_429
	s_mov_b64 s[12:13], exec
	buffer_wbl2 sc1
	buffer_inv sc1
	s_waitcnt lgkmcnt(0)
	s_waitcnt vmcnt(0)
	v_mbcnt_lo_u32_b32 v0, s12, 0
	v_mbcnt_hi_u32_b32 v0, s13, v0
	v_cmp_eq_u32_e32 vcc, 0, v0
	s_and_saveexec_b64 s[14:15], vcc
	s_cbranch_execz .LBB0_412
	s_bcnt1_i32_b64 s12, s[12:13]
	v_readlane_b32 s4, v253, 26
	v_mov_b32_e32 v3, s12
	v_readlane_b32 s5, v253, 27
	s_nop 4
	global_atomic_add v3, v1, v3, s[4:5] sc0

; __device__ __forceinline__ unsigned xb_ld(unsigned* p)              { return __hip_atomic_load(p, __ATOMIC_RELAXED, __HIP_MEMORY_SCOPE_AGENT); }
; __device__ __forceinline__ unsigned xb_add(unsigned* p, unsigned v) { return __hip_atomic_fetch_add(p, v, __ATOMIC_RELAXED, __HIP_MEMORY_SCOPE_AGENT); }
; #define XB_SPIN(cond, bar) do { unsigned _sp = 0; while (cond) { __builtin_amdgcn_s_sleep(1); \
;     if ((++_sp & 255u) == 0u) { if (xb_ld(&(bar)[XB_TMO])) break; if (_sp > XB_SPIN_CAP) { atomicAdd(&(bar)[XB_TMO], 1u); break; } } } } while (0)
; __device__ __forceinline__ void xcd_barrier(const XcdBarrier& b) {
;     ...
;             else XB_SPIN(xb_ld(&bar[XB_TOPGEN]) == tg, bar);
;             __builtin_amdgcn_fence(__ATOMIC_ACQUIRE, "agent");
;             xb_add(&bar[XB_XGEN(b.x)], 1u);
.LBB0_426:
	s_or_b64 exec, exec, s[12:13]
	s_mov_b64 s[12:13], exec
	v_mbcnt_lo_u32_b32 v0, s12, 0
	v_mbcnt_hi_u32_b32 v0, s13, v0
	v_cmp_eq_u32_e32 vcc, 0, v0
	s_waitcnt vmcnt(0)
	s_and_saveexec_b64 s[14:15], vcc
	s_cbranch_execz .LBB0_428
	s_bcnt1_i32_b64 s12, s[12:13]
	v_mov_b32_e32 v0, s12
	v_mov_b32_e32 v2, 0x2000
	global_atomic_add v2, v0, s[10:11] offset:1024

; __device__ __forceinline__ unsigned xb_ld(unsigned* p)              { return __hip_atomic_load(p, __ATOMIC_RELAXED, __HIP_MEMORY_SCOPE_AGENT); }
; __device__ __forceinline__ unsigned xb_add(unsigned* p, unsigned v) { return __hip_atomic_fetch_add(p, v, __ATOMIC_RELAXED, __HIP_MEMORY_SCOPE_AGENT); }
; #define XB_SPIN(cond, bar) do { unsigned _sp = 0; while (cond) { __builtin_amdgcn_s_sleep(1); \
;     if ((++_sp & 255u) == 0u) { if (xb_ld(&(bar)[XB_TMO])) break; if (_sp > XB_SPIN_CAP) { atomicAdd(&(bar)[XB_TMO], 1u); break; } } } } while (0)
; __device__ __forceinline__ void xcd_barrier(const XcdBarrier& b) {
;     ...
;         const unsigned old = xb_add(&bar[XB_XSUB(b.x)], 1u);
;         const unsigned gen = old / nloc;
;         if (old + 1u == (gen + 1u) * nloc) {
;     ...
;             XB_SPIN(xb_ld(&bar[XB_XGEN(b.x)]) == gen, bar);
.LBB0_512:
	s_or_b64 exec, exec, s[10:11]
	v_cvt_f32_u32_e32 v21, v3
	s_waitcnt vmcnt(0)
	v_readfirstlane_b32 s8, v20
	v_sub_u32_e32 v20, 0, v3
	v_rcp_iflag_f32_e32 v21, v21
	v_add_u32_e32 v22, s8, v0
	v_mul_f32_e32 v21, 0x4f7ffffe, v21
	v_cvt_u32_f32_e32 v21, v21
	v_mul_lo_u32 v0, v20, v21
	v_mul_hi_u32 v0, v21, v0
	v_add_u32_e32 v0, v21, v0
	v_mul_hi_u32 v0, v22, v0
	v_mul_lo_u32 v20, v0, v3
	v_sub_u32_e32 v20, v22, v20
	v_add_u32_e32 v21, 1, v0
	v_cmp_ge_u32_e32 vcc, v20, v3
	s_nop 1
	v_cndmask_b32_e32 v0, v0, v21, vcc
	v_sub_u32_e32 v21, v20, v3
	v_cndmask_b32_e32 v20, v20, v21, vcc
	v_add_u32_e32 v21, 1, v0
	v_cmp_ge_u32_e32 vcc, v20, v3
	v_add_u32_e32 v20, 1, v22
	s_nop 0
	v_cndmask_b32_e32 v0, v0, v21, vcc
	v_mul_lo_u32 v21, v3, v0
	v_add_u32_e32 v3, v21, v3
	v_cmp_ne_u32_e32 vcc, v20, v3
	s_and_saveexec_b64 s[8:9], vcc
	s_xor_b64 s[8:9], exec, s[8:9]
	s_cbranch_execz .LBB0_526
	s_waitcnt lgkmcnt(0)
	v_mov_b32_e32 v2, 0x2000
	global_load_dword v2, v2, s[6:7] offset:1024 sc1
	buffer_inv sc1
	s_add_u32 s12, s6, 0x2400
	s_addc_u32 s13, s7, 0
	s_waitcnt vmcnt(0)
	v_cmp_eq_u32_e32 vcc, v2, v0
	s_and_saveexec_b64 s[10:11], vcc
	s_cbranch_execz .LBB0_525
	s_mov_b32 s22, 1
	s_mov_b64 s[14:15], 0
	s_branch .LBB0_516

; __device__ __forceinline__ unsigned xb_ld(unsigned* p)              { return __hip_atomic_load(p, __ATOMIC_RELAXED, __HIP_MEMORY_SCOPE_AGENT); }
; __device__ __forceinline__ unsigned xb_add(unsigned* p, unsigned v) { return __hip_atomic_fetch_add(p, v, __ATOMIC_RELAXED, __HIP_MEMORY_SCOPE_AGENT); }
; #define XB_SPIN(cond, bar) do { unsigned _sp = 0; while (cond) { __builtin_amdgcn_s_sleep(1); \
;     if ((++_sp & 255u) == 0u) { if (xb_ld(&(bar)[XB_TMO])) break; if (_sp > XB_SPIN_CAP) { atomicAdd(&(bar)[XB_TMO], 1u); break; } } } } while (0)
; __device__ __forceinline__ void xcd_barrier(const XcdBarrier& b) {
;     ...
;             __builtin_amdgcn_fence(__ATOMIC_RELEASE, "agent");
;             asm volatile("s_waitcnt vmcnt(0)" ::: "memory");
;             const unsigned og = xb_add(&bar[XB_TOP], 1u);
;     ...
;             XB_SPIN(xb_ld(&bar[XB_XGEN(b.x)]) == gen, bar);
;             __builtin_amdgcn_fence(__ATOMIC_ACQUIRE, "agent");
;             asm volatile("s_waitcnt vmcnt(0)" ::: "memory");
.LBB0_525:
	s_or_b64 exec, exec, s[10:11]
	s_waitcnt vmcnt(0)
	s_waitcnt vmcnt(0)
.LBB0_526:
	s_andn2_saveexec_b64 s[8:9], s[8:9]
	s_cbranch_execz .LBB0_546
	s_mov_b64 s[8:9], exec
	buffer_wbl2 sc1
	buffer_inv sc1
	s_waitcnt lgkmcnt(0)
	s_waitcnt vmcnt(0)
	v_mbcnt_lo_u32_b32 v0, s8, 0
	v_mbcnt_hi_u32_b32 v0, s9, v0
	v_cmp_eq_u32_e32 vcc, 0, v0
	s_and_saveexec_b64 s[10:11], vcc
	s_cbranch_execz .LBB0_529
	s_bcnt1_i32_b64 s8, s[8:9]
	v_readlane_b32 s4, v253, 26
	v_mov_b32_e32 v3, s8
	v_readlane_b32 s5, v253, 27
	s_nop 4
	global_atomic_add v3, v1, v3, s[4:5] sc0

; __device__ __forceinline__ unsigned xb_ld(unsigned* p)              { return __hip_atomic_load(p, __ATOMIC_RELAXED, __HIP_MEMORY_SCOPE_AGENT); }
; __device__ __forceinline__ unsigned xb_add(unsigned* p, unsigned v) { return __hip_atomic_fetch_add(p, v, __ATOMIC_RELAXED, __HIP_MEMORY_SCOPE_AGENT); }
; #define XB_SPIN(cond, bar) do { unsigned _sp = 0; while (cond) { __builtin_amdgcn_s_sleep(1); \
;     if ((++_sp & 255u) == 0u) { if (xb_ld(&(bar)[XB_TMO])) break; if (_sp > XB_SPIN_CAP) { atomicAdd(&(bar)[XB_TMO], 1u); break; } } } } while (0)
; __device__ __forceinline__ void xcd_barrier(const XcdBarrier& b) {
;     ...
;             else XB_SPIN(xb_ld(&bar[XB_TOPGEN]) == tg, bar);
;             __builtin_amdgcn_fence(__ATOMIC_ACQUIRE, "agent");
;             xb_add(&bar[XB_XGEN(b.x)], 1u);
.LBB0_543:
	s_or_b64 exec, exec, s[8:9]
	s_mov_b64 s[8:9], exec
	v_mbcnt_lo_u32_b32 v0, s8, 0
	v_mbcnt_hi_u32_b32 v0, s9, v0
	v_cmp_eq_u32_e32 vcc, 0, v0
	s_waitcnt vmcnt(0)
	s_and_saveexec_b64 s[10:11], vcc
	s_cbranch_execz .LBB0_545
	s_bcnt1_i32_b64 s8, s[8:9]
	v_mov_b32_e32 v0, s8
	v_mov_b32_e32 v2, 0x2000
	global_atomic_add v2, v0, s[6:7] offset:1024

; __device__ __forceinline__ unsigned xb_add(unsigned* p, unsigned v) { return __hip_atomic_fetch_add(p, v, __ATOMIC_RELAXED, __HIP_MEMORY_SCOPE_AGENT); }
; __device__ __forceinline__ void xcd_barrier(const XcdBarrier& b) {
;     ...
;         if (old + 1u == (gen + 1u) * nloc) {
;             __builtin_amdgcn_fence(__ATOMIC_RELEASE, "agent");
;             asm volatile("s_waitcnt vmcnt(0)" ::: "memory");
;             const unsigned og = xb_add(&bar[XB_TOP], 1u);
.LBB0_834:
	s_andn2_saveexec_b64 s[8:9], s[8:9]
	s_cbranch_execz .LBB0_854
	s_mov_b64 s[8:9], exec
	buffer_wbl2 sc1
	buffer_inv sc1
	s_waitcnt lgkmcnt(0)
	s_waitcnt vmcnt(0)
	v_mbcnt_lo_u32_b32 v0, s8, 0
	v_mbcnt_hi_u32_b32 v0, s9, v0
	v_cmp_eq_u32_e32 vcc, 0, v0
	s_and_saveexec_b64 s[10:11], vcc
	s_cbranch_execz .LBB0_837
	s_bcnt1_i32_b64 s8, s[8:9]
	v_mov_b32_e32 v3, s8
	v_readlane_b32 s8, v253, 26
	v_readlane_b32 s9, v253, 27
	s_nop 4
	global_atomic_add v3, v1, v3, s[8:9] sc0

; __device__ __forceinline__ unsigned xb_ld(unsigned* p)              { return __hip_atomic_load(p, __ATOMIC_RELAXED, __HIP_MEMORY_SCOPE_AGENT); }
; __device__ __forceinline__ unsigned xb_add(unsigned* p, unsigned v) { return __hip_atomic_fetch_add(p, v, __ATOMIC_RELAXED, __HIP_MEMORY_SCOPE_AGENT); }
; #define XB_SPIN(cond, bar) do { unsigned _sp = 0; while (cond) { __builtin_amdgcn_s_sleep(1); \
;     if ((++_sp & 255u) == 0u) { if (xb_ld(&(bar)[XB_TMO])) break; if (_sp > XB_SPIN_CAP) { atomicAdd(&(bar)[XB_TMO], 1u); break; } } } } while (0)
; __device__ __forceinline__ void xcd_barrier(const XcdBarrier& b) {
;     ...
;             else XB_SPIN(xb_ld(&bar[XB_TOPGEN]) == tg, bar);
;             __builtin_amdgcn_fence(__ATOMIC_ACQUIRE, "agent");
;             xb_add(&bar[XB_XGEN(b.x)], 1u);
.LBB0_1090:
	s_or_b64 exec, exec, s[6:7]
	s_mov_b64 s[6:7], exec
	v_mbcnt_lo_u32_b32 v0, s6, 0
	v_mbcnt_hi_u32_b32 v0, s7, v0
	v_cmp_eq_u32_e32 vcc, 0, v0
	s_waitcnt vmcnt(0)
	s_and_saveexec_b64 s[8:9], vcc
	s_cbranch_execz .LBB0_206
	s_bcnt1_i32_b64 s6, s[6:7]
	v_mov_b32_e32 v0, s6
	v_mov_b32_e32 v2, 0x2000
	global_atomic_add v2, v0, s[4:5] offset:1024
	s_branch .LBB0_206
